# code placement: one 4-byte pad at the end of the mixer phase (all later phases shifted by 4 bytes)
# speedup vs baseline: 1.0023x; 1.0023x over previous
; #define PG8_LAS __attribute__((address_space(3)))
; __device__ __forceinline__ void xcd_barrier(const XcdBarrier& b) {
;     asm volatile("s_waitcnt vmcnt(0)" ::: "memory");
;     __syncthreads();
;     if (pg8::wg_tid((PG8_LAS unsigned char*)b.st - (LDS_BYTES - 16)) == 0) {
;         unsigned* bar = b.bar;
;         __builtin_amdgcn_s_waitcnt(0);
;         unsigned nloc = b.st[0], nx = b.st[1];
;         if (nloc == 0u) { xcd_barrier_complete(bar, b.x, nloc, nx); b.st[0] = nloc; b.st[1] = nx; }
.LBB0_619:
	s_nop 0
	s_waitcnt vmcnt(0)
	s_barrier
	s_getreg_b32 s3, hwreg(HW_REG_HW_ID, 0, 6)
	s_and_b32 s3, s3, 63
	s_lshl_b32 s3, s3, 2
	s_add_i32 s3, s3, 0
	s_add_i32 s3, s3, 0x27ef0
	v_mov_b32_e32 v0, s3
	ds_read_b32 v0, v0
	s_waitcnt lgkmcnt(0)
	v_readfirstlane_b32 s3, v0
	s_nop 1
	v_lshl_add_u32 v0, s3, 6, v213
	s_nop 0
	v_cmp_eq_u32_e32 vcc, 0, v0
	s_and_saveexec_b64 s[4:5], vcc
	s_cbranch_execz .LBB0_671
	v_mov_b32_e32 v0, s78
	s_waitcnt vmcnt(0) expcnt(0) lgkmcnt(0)
	ds_read_b32 v2, v0
	v_mov_b32_e32 v0, s79
	ds_read_b32 v0, v0
	s_waitcnt lgkmcnt(1)
	v_cmp_ne_u32_e32 vcc, 0, v2
	s_cbranch_vccnz .LBB0_635
	s_mov_b32 s3, 1
	s_branch .LBB0_623
